# swa K/V band staging: 8 masked loads issued together (was 8 serialized round trips); moba_list kmean fragment loads hoisted
# baseline (speedup 1.0000x reference)
; __device__ __forceinline__ int opq(int v) { asm volatile("" : "+v"(v)); return v; }
; __device__ __forceinline__ int lane_id() { return (int)__builtin_amdgcn_mbcnt_hi(~0u, __builtin_amdgcn_mbcnt_lo(~0u, 0u)); }
; __device__ __forceinline__ void moba_list_item(const Ptrs& P, int bh, int j) {
;     const int tid = opq((P.wave << 6) | lane_id()), lane = tid & 63, wid = __builtin_amdgcn_readfirstlane(tid >> 6), r32 = lane & 31, hi = lane >> 5;
;     const int b = bh >> 3, h = bh & 7, t = j * 256 + 32 * wid + r32;
;     bf16x8 qr[8]; moba_load_q(qr, P, (size_t)(b * SEQ + t), h, hi);
;     f32x16 ga = {};
; #pragma unroll
;     for (int ks = 0; ks < 8; ++ks) { const bf16x8 kf = *(const bf16x8*)(P.KM() + ((size_t)(bh * 16 + (r32 & 15))) * 128 + ks * 16 + hi * 8);
;         ga = __builtin_amdgcn_mfma_f32_32x32x16_bf16(kf, qr[ks], ga, 0, 0, 0); }
;     float g[16];
; #pragma unroll
;     for (int e = 0; e < 8; ++e) { const float mine = ga[e], oth = __shfl_xor(mine, 32);
;         const float lo = hi ? oth : mine, hh = hi ? mine : oth;
;         g[(e & 3) + 8 * (e >> 2)] = lo; g[4 + (e & 3) + 8 * (e >> 2)] = hh; }
;     const float NI = -3.0e38f;
;     unsigned sel = 0u;
; #pragma unroll
;     for (int pass = 0; pass < 3; ++pass) { float best = NI; int bi = -1;
; #pragma unroll
;         for (int n = 0; n < 16; ++n) { const bool ok = (n < j) && (((sel >> n) & 1u) == 0u) && (g[n] > best); best = ok ? g[n] : best; bi = ok ? n : bi; }
.LBB0_758:
	s_and_b32 s0, s75, 15
	s_cmp_eq_u32 s0, 0
	s_cbranch_scc1 .LBB0_757
	s_and_b32 s2, s75, -16
	s_ashr_i32 s3, s2, 31
	s_lshl_b64 s[4:5], s[2:3], 2
	s_add_u32 s26, s40, s4
	s_addc_u32 s27, s41, s5
	s_lshl_b64 s[2:3], s[2:3], 14
	v_mov_b32_e32 v23, v19
	s_add_u32 s28, s42, s2
	s_addc_u32 s29, s43, s3
	v_readfirstlane_b32 s2, v23
	s_ashr_i32 s2, s2, 1
	s_lshl_b32 s3, s0, 8
	s_andn2_b32 s2, s2, 31
	s_ashr_i32 s1, s75, 4
	s_add_i32 s2, s2, s3
	v_and_or_b32 v21, v23, 31, s2
	s_lshl_b32 s2, s1, 9
	s_and_b32 s2, s2, 0xfffff000
	v_add_u32_e32 v6, s2, v21
	s_lshl_b32 s1, s1, 8
	v_mov_b64_e32 v[4:5], s[14:15]
	s_and_b32 s20, s1, 0x700
	v_lshrrev_b32_e32 v2, 1, v23
	v_mad_i64_i32 v[4:5], s[2:3], v6, s64, v[4:5]
	v_mov_b64_e32 v[0:1], s[22:23]
	v_and_b32_e32 v16, 16, v2
	v_lshl_add_u64 v[4:5], v[4:5], 0, s[20:21]
	v_mad_i64_i32 v[0:1], s[2:3], v6, s64, v[0:1]
	v_lshl_add_u64 v[4:5], v[4:5], 0, v[16:17]
	v_lshl_add_u64 v[0:1], v[0:1], 0, s[20:21]
	v_add_co_u32_e32 v4, vcc, s65, v4
	v_lshl_add_u64 v[0:1], v[0:1], 0, v[16:17]
	s_nop 0
	v_addc_co_u32_e32 v5, vcc, 0, v5, vcc
	global_load_dwordx4 v[0:3], v[0:1], off
	s_nop 0
	global_load_dwordx4 v[24:27], v[4:5], off offset:32
	global_load_dwordx4 v[28:31], v[4:5], off offset:64
	global_load_dwordx4 v[32:35], v[4:5], off offset:96
	global_load_dwordx4 v[36:39], v[4:5], off offset:128
	global_load_dwordx4 v[40:43], v[4:5], off offset:160
	global_load_dwordx4 v[44:47], v[4:5], off offset:192
	global_load_dwordx4 v[48:51], v[4:5], off offset:224
	v_bfi_b32 v4, 15, v23, s75
	v_ashrrev_i32_e32 v5, 31, v4
	v_lshlrev_b64 v[4:5], 8, v[4:5]
	v_lshl_add_u64 v[4:5], s[24:25], 0, v[4:5]
	v_lshl_add_u64 v[56:57], v[4:5], 0, v[16:17]
	global_load_dwordx4 v[4:7], v[56:57], off
	global_load_dwordx4 v[52:55], v[56:57], off offset:32
	global_load_dwordx4 v[204:207], v[56:57], off offset:64
	global_load_dwordx4 v[208:211], v[56:57], off offset:96
	global_load_dwordx4 v[212:215], v[56:57], off offset:128
	global_load_dwordx4 v[216:219], v[56:57], off offset:160
	global_load_dwordx4 v[220:223], v[56:57], off offset:192
	global_load_dwordx4 v[224:227], v[56:57], off offset:224
	s_and_b32 s76, s74, 15
	s_cmp_lg_u32 s0, 1
	s_cselect_b64 s[6:7], -1, 0
	s_mov_b32 s20, 0
	s_waitcnt vmcnt(7)
	v_mfma_f32_32x32x16_bf16 v[0:15], v[4:7], v[0:3], 0
	s_waitcnt vmcnt(6)
	v_mfma_f32_32x32x16_bf16 v[0:15], v[52:55], v[24:27], v[0:15]
	s_waitcnt vmcnt(5)
	v_mfma_f32_32x32x16_bf16 v[0:15], v[204:207], v[28:31], v[0:15]
	s_waitcnt vmcnt(4)
	v_mfma_f32_32x32x16_bf16 v[0:15], v[208:211], v[32:35], v[0:15]
	s_waitcnt vmcnt(3)
	v_mfma_f32_32x32x16_bf16 v[0:15], v[212:215], v[36:39], v[0:15]
	s_waitcnt vmcnt(2)
	v_mfma_f32_32x32x16_bf16 v[0:15], v[216:219], v[40:43], v[0:15]
	s_waitcnt vmcnt(1)
	v_mfma_f32_32x32x16_bf16 v[0:15], v[220:223], v[44:47], v[0:15]
	s_waitcnt vmcnt(0)
	v_mfma_f32_32x32x16_bf16 v[0:15], v[224:227], v[48:51], v[0:15]
	s_nop 11
	v_and_b32_e32 v8, 63, v23
	v_cmp_gt_u32_e64 s[2:3], 32, v8
	ds_bpermute_b32 v9, v18, v0
	s_waitcnt lgkmcnt(0)
	v_cndmask_b32_e64 v25, v9, v0, s[2:3]
	v_cndmask_b32_e64 v14, v0, v9, s[2:3]
	ds_bpermute_b32 v0, v18, v1
	v_cmp_nlt_f32_e32 vcc, s66, v25
	s_waitcnt lgkmcnt(0)
	v_cndmask_b32_e64 v24, v0, v1, s[2:3]
	v_cndmask_b32_e64 v13, v1, v0, s[2:3]
	ds_bpermute_b32 v0, v18, v2
	s_waitcnt lgkmcnt(0)
	v_cndmask_b32_e64 v16, v0, v2, s[2:3]
	v_cndmask_b32_e64 v12, v2, v0, s[2:3]
	ds_bpermute_b32 v0, v18, v3
	s_waitcnt lgkmcnt(0)
	v_cndmask_b32_e64 v15, v0, v3, s[2:3]
	v_cndmask_b32_e64 v11, v3, v0, s[2:3]
	ds_bpermute_b32 v0, v18, v4
	ds_bpermute_b32 v3, v18, v7
	s_waitcnt lgkmcnt(1)
	v_cndmask_b32_e64 v10, v0, v4, s[2:3]
	v_cndmask_b32_e64 v2, v4, v0, s[2:3]
	ds_bpermute_b32 v0, v18, v5
	s_waitcnt lgkmcnt(1)
	v_cndmask_b32_e64 v3, v3, v7, s[2:3]
	s_waitcnt lgkmcnt(0)
	v_cndmask_b32_e64 v9, v0, v5, s[2:3]
	v_cndmask_b32_e64 v1, v5, v0, s[2:3]
	ds_bpermute_b32 v0, v18, v6
	v_cndmask_b32_e64 v5, 0, -1, vcc
	s_waitcnt lgkmcnt(0)
	v_cndmask_b32_e64 v4, v0, v6, s[2:3]
	v_cndmask_b32_e64 v0, v6, v0, s[2:3]
	v_cndmask_b32_e32 v6, v25, v20, vcc
	v_cmp_gt_f32_e64 s[4:5], v24, v6
	s_and_b64 s[4:5], s[6:7], s[4:5]
	s_cmp_gt_u32 s0, 2
	v_cndmask_b32_e64 v6, v6, v24, s[4:5]
	v_cndmask_b32_e64 v5, v5, 1, s[4:5]
	s_cselect_b64 s[62:63], -1, 0
	v_cmp_gt_f32_e64 s[4:5], v16, v6
	s_and_b64 s[4:5], s[62:63], s[4:5]
	s_cmp_gt_u32 s0, 3
	v_cndmask_b32_e64 v6, v6, v16, s[4:5]
	v_cndmask_b32_e64 v5, v5, 2, s[4:5]
	s_cselect_b64 s[60:61], -1, 0
	v_cmp_gt_f32_e64 s[4:5], v15, v6
	s_and_b64 s[4:5], s[60:61], s[4:5]
	s_cmp_gt_u32 s0, 4
	v_cndmask_b32_e64 v6, v6, v15, s[4:5]
	v_cndmask_b32_e64 v5, v5, 3, s[4:5]
	s_cselect_b64 s[58:59], -1, 0
	v_cmp_gt_f32_e64 s[4:5], v14, v6
	s_and_b64 s[4:5], s[58:59], s[4:5]
	s_cmp_gt_u32 s0, 5
	v_cndmask_b32_e64 v6, v6, v14, s[4:5]
	v_cndmask_b32_e64 v5, v5, 4, s[4:5]
	s_cselect_b64 s[56:57], -1, 0
	v_cmp_gt_f32_e64 s[4:5], v13, v6
	s_and_b64 s[4:5], s[56:57], s[4:5]
	s_cmp_gt_u32 s0, 6
	v_cndmask_b32_e64 v6, v6, v13, s[4:5]
	v_cndmask_b32_e64 v5, v5, 5, s[4:5]
	s_cselect_b64 s[54:55], -1, 0
	v_cmp_gt_f32_e64 s[4:5], v12, v6
	s_and_b64 s[4:5], s[54:55], s[4:5]
	s_cmp_gt_u32 s0, 7
	v_cndmask_b32_e64 v6, v6, v12, s[4:5]
	v_cndmask_b32_e64 v5, v5, 6, s[4:5]
	s_cselect_b64 s[52:53], -1, 0
	v_cmp_gt_f32_e64 s[4:5], v11, v6
	s_and_b64 s[4:5], s[52:53], s[4:5]
	s_cmp_gt_u32 s0, 8
	v_cndmask_b32_e64 v6, v6, v11, s[4:5]
	v_cndmask_b32_e64 v5, v5, 7, s[4:5]
	s_cselect_b64 s[50:51], -1, 0
	v_cmp_gt_f32_e64 s[4:5], v10, v6
	s_and_b64 s[4:5], s[50:51], s[4:5]
	s_cmp_gt_u32 s0, 9
	v_cndmask_b32_e64 v6, v6, v10, s[4:5]
	v_cndmask_b32_e64 v5, v5, 8, s[4:5]
	s_cselect_b64 s[48:49], -1, 0
; __device__ __forceinline__ void moba_list_item(const Ptrs& P, int bh, int j) {
;     ...
;     for (int pass = 0; pass < 3; ++pass) { float best = NI; int bi = -1;
; #pragma unroll
;         for (int n = 0; n < 16; ++n) { const bool ok = (n < j) && (((sel >> n) & 1u) == 0u) && (g[n] > best); best = ok ? g[n] : best; bi = ok ? n : bi; }
;         if (bi >= 0) sel |= 1u << bi; }
	v_cmp_gt_f32_e64 s[4:5], v9, v6
	s_and_b64 s[4:5], s[48:49], s[4:5]
	s_cmp_gt_u32 s0, 10
	v_cndmask_b32_e64 v6, v6, v9, s[4:5]
	v_cndmask_b32_e64 v5, v5, 9, s[4:5]
	s_cselect_b64 s[46:47], -1, 0
	v_cmp_gt_f32_e64 s[4:5], v4, v6
	s_and_b64 s[4:5], s[46:47], s[4:5]
	s_cmp_gt_u32 s0, 11
	v_cndmask_b32_e64 v6, v6, v4, s[4:5]
	v_cndmask_b32_e64 v5, v5, 10, s[4:5]
	s_cselect_b64 s[44:45], -1, 0
	v_cmp_gt_f32_e64 s[4:5], v3, v6
	s_and_b64 s[4:5], s[44:45], s[4:5]
	s_cmp_gt_u32 s0, 12
	v_cndmask_b32_e64 v6, v6, v3, s[4:5]
	v_cndmask_b32_e64 v5, v5, 11, s[4:5]
	s_cselect_b64 s[36:37], -1, 0
	v_cmp_gt_f32_e64 s[4:5], v2, v6
	s_and_b64 s[4:5], s[36:37], s[4:5]
	s_cmp_gt_u32 s0, 13
	v_cndmask_b32_e64 v6, v6, v2, s[4:5]
	v_cndmask_b32_e64 v5, v5, 12, s[4:5]
	s_cselect_b64 s[34:35], -1, 0
	v_cmp_gt_f32_e64 s[4:5], v1, v6
	s_and_b64 s[4:5], s[34:35], s[4:5]
	s_cmp_eq_u32 s0, 15
	v_cndmask_b32_e64 v6, v6, v1, s[4:5]
	v_cndmask_b32_e64 v5, v5, 13, s[4:5]
	s_cselect_b64 s[30:31], -1, 0
	v_cmp_gt_f32_e64 s[4:5], v0, v6
	s_and_b64 s[0:1], s[30:31], s[4:5]
	v_cndmask_b32_e64 v5, v5, 14, s[0:1]
	v_lshlrev_b32_e64 v6, v5, 1
	v_cmp_lt_i32_e64 s[4:5], -1, v5
	s_nop 1
	v_cndmask_b32_e64 v5, 0, v6, s[4:5]
	v_and_b32_e32 v6, 1, v5
	v_cmp_eq_u32_e64 s[4:5], 1, v6
	s_or_b64 s[4:5], s[4:5], vcc
	v_and_b32_e32 v26, 2, v5
	v_cndmask_b32_e64 v6, 0, -1, s[4:5]
	v_cndmask_b32_e64 v7, v25, v20, s[4:5]
	v_cmp_eq_u32_e64 s[4:5], 0, v26
	s_and_b64 s[0:1], s[6:7], s[4:5]
	v_cmp_gt_f32_e64 s[4:5], v24, v7
	s_and_b64 s[4:5], s[0:1], s[4:5]
	v_and_b32_e32 v26, 4, v5
	v_cndmask_b32_e64 v6, v6, 1, s[4:5]
	v_cndmask_b32_e64 v7, v7, v24, s[4:5]
	v_cmp_eq_u32_e64 s[4:5], 0, v26
	s_and_b64 s[0:1], s[62:63], s[4:5]
	v_cmp_gt_f32_e64 s[4:5], v16, v7
	s_and_b64 s[4:5], s[0:1], s[4:5]
	v_and_b32_e32 v26, 8, v5
	v_cndmask_b32_e64 v6, v6, 2, s[4:5]
	v_cndmask_b32_e64 v7, v7, v16, s[4:5]
	v_cmp_eq_u32_e64 s[4:5], 0, v26
	s_and_b64 s[0:1], s[60:61], s[4:5]
	v_cmp_gt_f32_e64 s[4:5], v15, v7
	s_and_b64 s[4:5], s[0:1], s[4:5]
	v_and_b32_e32 v26, 16, v5
	v_cndmask_b32_e64 v6, v6, 3, s[4:5]
	v_cndmask_b32_e64 v7, v7, v15, s[4:5]
	v_cmp_eq_u32_e64 s[4:5], 0, v26
	s_and_b64 s[0:1], s[58:59], s[4:5]
	v_cmp_gt_f32_e64 s[4:5], v14, v7
	s_and_b64 s[4:5], s[0:1], s[4:5]
	v_and_b32_e32 v26, 32, v5
	v_cndmask_b32_e64 v6, v6, 4, s[4:5]
	v_cndmask_b32_e64 v7, v7, v14, s[4:5]
	v_cmp_eq_u32_e64 s[4:5], 0, v26
	s_and_b64 s[0:1], s[56:57], s[4:5]
	v_cmp_gt_f32_e64 s[4:5], v13, v7
	s_and_b64 s[4:5], s[0:1], s[4:5]
	v_and_b32_e32 v26, 64, v5
	v_cndmask_b32_e64 v6, v6, 5, s[4:5]
	v_cndmask_b32_e64 v7, v7, v13, s[4:5]
	v_cmp_eq_u32_e64 s[4:5], 0, v26
	s_and_b64 s[0:1], s[54:55], s[4:5]
	v_cmp_gt_f32_e64 s[4:5], v12, v7
	s_and_b64 s[4:5], s[0:1], s[4:5]
	v_and_b32_e32 v26, 0x80, v5
	v_cndmask_b32_e64 v6, v6, 6, s[4:5]
	v_cndmask_b32_e64 v7, v7, v12, s[4:5]
	v_cmp_eq_u32_e64 s[4:5], 0, v26
	s_and_b64 s[0:1], s[52:53], s[4:5]
	v_cmp_gt_f32_e64 s[4:5], v11, v7
	s_and_b64 s[4:5], s[0:1], s[4:5]
	v_and_b32_e32 v26, 0x100, v5
	v_cndmask_b32_e64 v6, v6, 7, s[4:5]
	v_cndmask_b32_e64 v7, v7, v11, s[4:5]
	v_cmp_eq_u32_e64 s[4:5], 0, v26
	s_and_b64 s[0:1], s[50:51], s[4:5]
	v_cmp_gt_f32_e64 s[4:5], v10, v7
	s_and_b64 s[4:5], s[0:1], s[4:5]
	v_and_b32_e32 v26, 0x200, v5
	v_cndmask_b32_e64 v6, v6, 8, s[4:5]
	v_cndmask_b32_e64 v7, v7, v10, s[4:5]
	v_cmp_eq_u32_e64 s[4:5], 0, v26
	s_and_b64 s[0:1], s[48:49], s[4:5]
	v_cmp_gt_f32_e64 s[4:5], v9, v7
	s_and_b64 s[4:5], s[0:1], s[4:5]
	v_and_b32_e32 v26, 0x400, v5
	v_cndmask_b32_e64 v6, v6, 9, s[4:5]
	v_cndmask_b32_e64 v7, v7, v9, s[4:5]
	v_cmp_eq_u32_e64 s[4:5], 0, v26
	s_and_b64 s[0:1], s[46:47], s[4:5]
	v_cmp_gt_f32_e64 s[4:5], v4, v7
	s_and_b64 s[4:5], s[0:1], s[4:5]
	v_and_b32_e32 v26, 0x800, v5
	v_cndmask_b32_e64 v6, v6, 10, s[4:5]
	v_cndmask_b32_e64 v7, v7, v4, s[4:5]
	v_cmp_eq_u32_e64 s[4:5], 0, v26
	s_and_b64 s[0:1], s[44:45], s[4:5]
	v_cmp_gt_f32_e64 s[4:5], v3, v7
	s_and_b64 s[4:5], s[0:1], s[4:5]
	v_and_b32_e32 v26, 0x1000, v5
	v_cndmask_b32_e64 v6, v6, 11, s[4:5]
	v_cndmask_b32_e64 v7, v7, v3, s[4:5]
	v_cmp_eq_u32_e64 s[4:5], 0, v26
	s_and_b64 s[0:1], s[36:37], s[4:5]
	v_cmp_gt_f32_e64 s[4:5], v2, v7
	s_and_b64 s[4:5], s[0:1], s[4:5]
	v_and_b32_e32 v26, 0x2000, v5
	v_cndmask_b32_e64 v6, v6, 12, s[4:5]
	v_cndmask_b32_e64 v7, v7, v2, s[4:5]
	v_cmp_eq_u32_e64 s[4:5], 0, v26
; __device__ __forceinline__ void moba_list_item(const Ptrs& P, int bh, int j) {
;     ...
;     for (int pass = 0; pass < 3; ++pass) { float best = NI; int bi = -1;
; #pragma unroll
;         for (int n = 0; n < 16; ++n) { const bool ok = (n < j) && (((sel >> n) & 1u) == 0u) && (g[n] > best); best = ok ? g[n] : best; bi = ok ? n : bi; }
;         if (bi >= 0) sel |= 1u << bi; }
;     for (int n = 0; n < j; ++n) {
	s_and_b64 s[0:1], s[34:35], s[4:5]
	v_cmp_gt_f32_e64 s[4:5], v1, v7
	s_and_b64 s[4:5], s[0:1], s[4:5]
	v_and_b32_e32 v26, 0x4000, v5
	v_cndmask_b32_e64 v6, v6, 13, s[4:5]
	v_cndmask_b32_e64 v7, v7, v1, s[4:5]
	v_cmp_eq_u32_e64 s[4:5], 0, v26
	s_and_b64 s[0:1], s[30:31], s[4:5]
	v_cmp_gt_f32_e64 s[4:5], v0, v7
	s_and_b64 s[0:1], s[0:1], s[4:5]
	v_cndmask_b32_e64 v6, v6, 14, s[0:1]
	v_lshlrev_b32_e64 v7, v6, 1
	v_cmp_lt_i32_e64 s[4:5], -1, v6
	s_nop 1
	v_cndmask_b32_e64 v6, 0, v7, s[4:5]
	v_or_b32_e32 v7, v6, v5
	v_and_b32_e32 v26, 1, v7
	v_cmp_eq_u32_e64 s[4:5], 1, v26
	s_or_b64 vcc, s[4:5], vcc
	v_bitop3_b32 v27, v6, 2, v5 bitop3:0xc8
	v_cndmask_b32_e64 v26, 0, -1, vcc
	v_cndmask_b32_e32 v25, v25, v20, vcc
	v_cmp_eq_u32_e32 vcc, 0, v27
	s_and_b64 s[0:1], s[6:7], vcc
	v_cmp_gt_f32_e32 vcc, v24, v25
	s_and_b64 vcc, s[0:1], vcc
	v_cmp_eq_u32_e64 s[4:5], 0, v8
	v_cndmask_b32_e32 v24, v25, v24, vcc
	v_bitop3_b32 v25, v6, 4, v5 bitop3:0xc8
	v_cndmask_b32_e64 v26, v26, 1, vcc
	v_cmp_eq_u32_e32 vcc, 0, v25
	s_and_b64 s[0:1], s[62:63], vcc
	v_cmp_gt_f32_e32 vcc, v16, v24
	s_and_b64 vcc, s[0:1], vcc
	s_nop 0
	v_cndmask_b32_e32 v16, v24, v16, vcc
	v_bitop3_b32 v24, v6, 8, v5 bitop3:0xc8
	v_cndmask_b32_e64 v25, v26, 2, vcc
	v_cmp_eq_u32_e32 vcc, 0, v24
	s_and_b64 s[0:1], s[60:61], vcc
	v_cmp_gt_f32_e32 vcc, v15, v16
	s_and_b64 vcc, s[0:1], vcc
	s_nop 0
	v_cndmask_b32_e32 v15, v16, v15, vcc
	v_bitop3_b32 v16, v6, 16, v5 bitop3:0xc8
	v_cndmask_b32_e64 v24, v25, 3, vcc
	v_cmp_eq_u32_e32 vcc, 0, v16
	s_and_b64 s[0:1], s[58:59], vcc
	v_cmp_gt_f32_e32 vcc, v14, v15
	s_and_b64 vcc, s[0:1], vcc
	s_nop 0
	v_cndmask_b32_e32 v14, v15, v14, vcc
	v_bitop3_b32 v15, v6, 32, v5 bitop3:0xc8
	v_cndmask_b32_e64 v16, v24, 4, vcc
	v_cmp_eq_u32_e32 vcc, 0, v15
	s_and_b64 s[0:1], s[56:57], vcc
	v_cmp_gt_f32_e32 vcc, v13, v14
	s_and_b64 vcc, s[0:1], vcc
	s_nop 0
	v_cndmask_b32_e32 v13, v14, v13, vcc
	v_bitop3_b32 v14, v6, 64, v5 bitop3:0xc8
	v_cndmask_b32_e64 v15, v16, 5, vcc
	v_cmp_eq_u32_e32 vcc, 0, v14
	s_and_b64 s[0:1], s[54:55], vcc
	v_cmp_gt_f32_e32 vcc, v12, v13
	s_and_b64 vcc, s[0:1], vcc
	s_nop 0
	v_cndmask_b32_e32 v12, v13, v12, vcc
	v_bitop3_b32 v13, v6, s67, v5 bitop3:0xc8
	v_cndmask_b32_e64 v14, v15, 6, vcc
	v_cmp_eq_u32_e32 vcc, 0, v13
	s_and_b64 s[0:1], s[52:53], vcc
	v_cmp_gt_f32_e32 vcc, v11, v12
	s_and_b64 vcc, s[0:1], vcc
	s_nop 0
	v_cndmask_b32_e32 v11, v12, v11, vcc
	v_bitop3_b32 v12, v6, s68, v5 bitop3:0xc8
	v_cndmask_b32_e64 v13, v14, 7, vcc
	v_cmp_eq_u32_e32 vcc, 0, v12
	s_and_b64 s[0:1], s[50:51], vcc
	v_cmp_gt_f32_e32 vcc, v10, v11
	s_and_b64 vcc, s[0:1], vcc
	s_nop 0
	v_cndmask_b32_e32 v10, v11, v10, vcc
	v_bitop3_b32 v11, v6, s39, v5 bitop3:0xc8
	v_cndmask_b32_e64 v12, v13, 8, vcc
	v_cmp_eq_u32_e32 vcc, 0, v11
	s_and_b64 s[0:1], s[48:49], vcc
	v_cmp_gt_f32_e32 vcc, v9, v10
	s_and_b64 vcc, s[0:1], vcc
	s_nop 0
	v_cndmask_b32_e32 v9, v10, v9, vcc
	v_bitop3_b32 v10, v6, s69, v5 bitop3:0xc8
	v_cndmask_b32_e64 v11, v12, 9, vcc
	v_cmp_eq_u32_e32 vcc, 0, v10
	s_and_b64 s[0:1], s[46:47], vcc
	v_cmp_gt_f32_e32 vcc, v4, v9
	s_and_b64 vcc, s[0:1], vcc
	s_nop 0
	v_cndmask_b32_e32 v4, v9, v4, vcc
	v_bitop3_b32 v9, v6, s70, v5 bitop3:0xc8
	v_cndmask_b32_e64 v10, v11, 10, vcc
	v_cmp_eq_u32_e32 vcc, 0, v9
	s_and_b64 s[0:1], s[44:45], vcc
	v_cmp_gt_f32_e32 vcc, v3, v4
	s_and_b64 vcc, s[0:1], vcc
	s_nop 0
	v_cndmask_b32_e32 v3, v4, v3, vcc
	v_bitop3_b32 v4, v6, s71, v5 bitop3:0xc8
	v_cndmask_b32_e64 v9, v10, 11, vcc
	v_cmp_eq_u32_e32 vcc, 0, v4
	s_and_b64 s[0:1], s[36:37], vcc
	v_cmp_gt_f32_e32 vcc, v2, v3
	s_and_b64 vcc, s[0:1], vcc
	s_nop 0
	v_cndmask_b32_e32 v2, v3, v2, vcc
	v_bitop3_b32 v3, v6, s72, v5 bitop3:0xc8
	v_cndmask_b32_e64 v4, v9, 12, vcc
	v_cmp_eq_u32_e32 vcc, 0, v3
	s_and_b64 s[0:1], s[34:35], vcc
	v_cmp_gt_f32_e32 vcc, v1, v2
	s_and_b64 vcc, s[0:1], vcc
	s_nop 0
	v_cndmask_b32_e32 v1, v2, v1, vcc
	v_bitop3_b32 v2, v6, s73, v5 bitop3:0xc8
	v_cndmask_b32_e64 v3, v4, 13, vcc
	v_cmp_eq_u32_e32 vcc, 0, v2
	s_and_b64 s[0:1], s[30:31], vcc
	v_cmp_gt_f32_e32 vcc, v0, v1
	s_and_b64 s[0:1], s[0:1], vcc
	v_cndmask_b32_e64 v0, v3, 14, s[0:1]
	v_lshlrev_b32_e64 v1, v0, 1
	v_cmp_lt_i32_e32 vcc, -1, v0
	s_nop 1
	v_cndmask_b32_e32 v0, 0, v1, vcc
	v_or_b32_e32 v2, v0, v7
	v_lshlrev_b64 v[0:1], v23, -1
	v_not_b32_e32 v1, v1
	v_not_b32_e32 v0, v0
	v_mov_b32_e32 v200, 0

; #define LAS __attribute__((address_space(3)))
; __device__ __forceinline__ void swa_item(LAS unsigned char* lds, const Ptrs& P, int l, int b, int hk, int qblk) {
;     ...
;     const int kvbase = qblk * 128 - 128;
; #pragma unroll
;     for (int i = 0; i < 4; ++i) { const int r = (tid >> 3) + 64 * i, c8 = tid & 7, kv = kvbase + r;
;         u32x4 w = {0u, 0u, 0u, 0u};
;         if (kv >= 0) w = *(const u32x4*)(P.PA() + (size_t)(b * SEQ + kv) * NA + C_KB + hk * 64 + c8 * 8);
;         *(LAS u32x4*)(kb + r * 144 + c8 * 16) = w; }
; #pragma unroll
;     for (int i = 0; i < 4; ++i) { const int d = (tid >> 5) + 16 * i, k8 = tid & 31, kv = kvbase + k8 * 8;
;         u32x4 w = {0u, 0u, 0u, 0u};
;         if (kv >= 0) w = *(const u32x4*)(P.VTB() + ((size_t)((b * 4 + hk) * 64 + d)) * SEQ + kv);
;         *(LAS u32x2*)(vb + d * 520 + k8 * 16) = (u32x2){w.x, w.y}; *(LAS u32x2*)(vb + d * 520 + k8 * 16 + 8) = (u32x2){w.z, w.w}; }
;     { const int g = tid >> 7, dist = tid & 127; lut[tid] = P.rpe[t5_bucket(dist) * 24 + 8 + hk * 4 + g] * LOG2E; }
.LBB0_786:
	s_and_b32 s3, s38, 31
	v_mov_b32_e32 v6, v131
	s_lshl_b32 s24, s3, 7
	s_add_i32 s48, s24, 0xffffff80
	v_ashrrev_i32_e32 v10, 3, v6
	s_ashr_i32 s27, s38, 7
	s_bfe_u32 s26, s38, 0x20005
	v_and_b32_e32 v4, 7, v6
	v_add_u32_e32 v8, s48, v10
	v_readfirstlane_b32 s2, v6
	s_lshl_b32 s25, s27, 12
	s_lshl_b32 s49, s26, 6
	v_lshlrev_b32_e32 v7, 3, v4
	s_lshl_b32 s6, s49, 1
	v_lshlrev_b32_e32 v96, 1, v7
	v_mov_b32_e32 v12, 0
	v_mov_b32_e32 v13, 0
	v_mov_b32_e32 v14, 0
	v_mov_b32_e32 v15, 0
	v_mov_b32_e32 v16, 0
	v_mov_b32_e32 v17, 0
	v_mov_b32_e32 v18, 0
	v_mov_b32_e32 v19, 0
	v_mov_b32_e32 v20, 0
	v_mov_b32_e32 v21, 0
	v_mov_b32_e32 v22, 0
	v_mov_b32_e32 v23, 0
	v_mov_b32_e32 v24, 0
	v_mov_b32_e32 v25, 0
	v_mov_b32_e32 v26, 0
	v_mov_b32_e32 v27, 0
	v_mov_b32_e32 v28, 0
	v_mov_b32_e32 v29, 0
	v_mov_b32_e32 v30, 0
	v_mov_b32_e32 v31, 0
	v_mov_b32_e32 v32, 0
	v_mov_b32_e32 v33, 0
	v_mov_b32_e32 v34, 0
	v_mov_b32_e32 v35, 0
	v_mov_b32_e32 v36, 0
	v_mov_b32_e32 v37, 0
	v_mov_b32_e32 v38, 0
	v_mov_b32_e32 v39, 0
	v_mov_b32_e32 v40, 0
	v_mov_b32_e32 v41, 0
	v_mov_b32_e32 v42, 0
	v_mov_b32_e32 v43, 0
	v_mov_b32_e32 v3, v8
	v_cmp_lt_i32_e32 vcc, -1, v3
	s_and_saveexec_b64 s[0:1], vcc
	s_cbranch_execz .Lswa_k0_l0
	v_add_u32_e32 v2, s25, v3
	v_mov_b64_e32 v[0:1], s[14:15]
	v_mad_i64_i32 v[0:1], s[50:51], v2, s18, v[0:1]
	v_lshl_add_u64 v[0:1], v[0:1], 0, s[6:7]
	v_lshl_add_u64 v[0:1], v[0:1], 0, v[96:97]
	v_add_co_u32_e32 v0, vcc, 0xef02000, v0
	s_nop 1
	v_addc_co_u32_e32 v1, vcc, 0, v1, vcc
	global_load_dwordx4 v[12:15], v[0:1], off offset:2048
.Lswa_k0_l0:
	s_or_b64 exec, exec, s[0:1]
	v_add_u32_e32 v3, 64, v8
	v_cmp_lt_i32_e32 vcc, -1, v3
	s_and_saveexec_b64 s[0:1], vcc
	s_cbranch_execz .Lswa_k1_l0
	v_add_u32_e32 v2, s25, v3
	v_mov_b64_e32 v[0:1], s[14:15]
	v_mad_i64_i32 v[0:1], s[50:51], v2, s18, v[0:1]
	v_lshl_add_u64 v[0:1], v[0:1], 0, s[6:7]
	v_lshl_add_u64 v[0:1], v[0:1], 0, v[96:97]
	v_add_co_u32_e32 v0, vcc, 0xef02000, v0
	s_nop 1
	v_addc_co_u32_e32 v1, vcc, 0, v1, vcc
	global_load_dwordx4 v[16:19], v[0:1], off offset:2048
.Lswa_k1_l0:
	s_or_b64 exec, exec, s[0:1]
	v_add_u32_e32 v3, 128, v8
	v_cmp_lt_i32_e32 vcc, -1, v3
	s_and_saveexec_b64 s[0:1], vcc
	s_cbranch_execz .Lswa_k2_l0
	v_add_u32_e32 v2, s25, v3
	v_mov_b64_e32 v[0:1], s[14:15]
	v_mad_i64_i32 v[0:1], s[50:51], v2, s18, v[0:1]
	v_lshl_add_u64 v[0:1], v[0:1], 0, s[6:7]
	v_lshl_add_u64 v[0:1], v[0:1], 0, v[96:97]
	v_add_co_u32_e32 v0, vcc, 0xef02000, v0
	s_nop 1
	v_addc_co_u32_e32 v1, vcc, 0, v1, vcc
	global_load_dwordx4 v[20:23], v[0:1], off offset:2048
.Lswa_k2_l0:
	s_or_b64 exec, exec, s[0:1]
	v_add_u32_e32 v3, 192, v8
	v_cmp_lt_i32_e32 vcc, -1, v3
	s_and_saveexec_b64 s[0:1], vcc
	s_cbranch_execz .Lswa_k3_l0
	v_add_u32_e32 v2, s25, v3
	v_mov_b64_e32 v[0:1], s[14:15]
	v_mad_i64_i32 v[0:1], s[50:51], v2, s18, v[0:1]
	v_lshl_add_u64 v[0:1], v[0:1], 0, s[6:7]
	v_lshl_add_u64 v[0:1], v[0:1], 0, v[96:97]
	v_add_co_u32_e32 v0, vcc, 0xef02000, v0
	s_nop 1
	v_addc_co_u32_e32 v1, vcc, 0, v1, vcc
	global_load_dwordx4 v[24:27], v[0:1], off offset:2048
.Lswa_k3_l0:
	s_or_b64 exec, exec, s[0:1]
	v_lshl_add_u32 v4, v4, 4, 0
	v_mul_lo_u32 v5, v10, s28
	v_add_u32_e32 v9, v4, v5
	v_and_b32_e32 v133, 31, v6
	v_lshl_add_u32 v96, v133, 3, s48
	s_lshl_b32 s0, s27, 8
	v_ashrrev_i32_e32 v7, 5, v6
	s_or_b32 s6, s49, s0
	v_cmp_lt_i32_e32 vcc, -1, v96
	s_and_saveexec_b64 s[0:1], vcc
	s_cbranch_execz .Lswa_v_l0
	v_add_u32_e32 v0, s6, v7
	v_ashrrev_i32_e32 v1, 31, v0
	v_lshlrev_b64 v[0:1], 13, v[0:1]
	v_lshl_add_u64 v[0:1], s[4:5], 0, v[0:1]
	v_lshl_add_u64 v[0:1], v[96:97], 1, v[0:1]
	global_load_dwordx4 v[28:31], v[0:1], off
	v_add3_u32 v0, v7, s6, 16
	v_ashrrev_i32_e32 v1, 31, v0
	v_lshlrev_b64 v[0:1], 13, v[0:1]
	v_lshl_add_u64 v[0:1], s[4:5], 0, v[0:1]
	v_lshl_add_u64 v[0:1], v[96:97], 1, v[0:1]
	global_load_dwordx4 v[32:35], v[0:1], off
	v_add3_u32 v0, v7, s6, 32
	v_ashrrev_i32_e32 v1, 31, v0
	v_lshlrev_b64 v[0:1], 13, v[0:1]
	v_lshl_add_u64 v[0:1], s[4:5], 0, v[0:1]
	v_lshl_add_u64 v[0:1], v[96:97], 1, v[0:1]
	global_load_dwordx4 v[36:39], v[0:1], off
	v_add3_u32 v0, v7, s6, 48
	v_ashrrev_i32_e32 v1, 31, v0
	v_lshlrev_b64 v[0:1], 13, v[0:1]
	v_lshl_add_u64 v[0:1], s[4:5], 0, v[0:1]
	v_lshl_add_u64 v[0:1], v[96:97], 1, v[0:1]
	global_load_dwordx4 v[40:43], v[0:1], off
.Lswa_v_l0:
	s_or_b64 exec, exec, s[0:1]
	v_lshl_add_u32 v8, v133, 4, 0
	v_mul_lo_u32 v0, v7, s29
	v_add3_u32 v44, v8, v0, s30
	v_add3_u32 v45, v0, v8, s31
	v_add3_u32 v46, v8, v0, s34
	v_add3_u32 v47, v8, v0, s35
	s_waitcnt vmcnt(0)
	ds_write_b128 v9, v[12:15]
	ds_write_b128 v9, v[16:19] offset:9216
	ds_write_b128 v9, v[20:23] offset:18432
	ds_write_b128 v9, v[24:27] offset:27648
	ds_write2_b64 v44, v[28:29], v[30:31] offset1:1
	ds_write2_b64 v45, v[32:33], v[34:35] offset1:1
	ds_write2_b64 v46, v[36:37], v[38:39] offset1:1
	ds_write2_b64 v47, v[40:41], v[42:43] offset1:1
	v_and_b32_e32 v0, 0x7f, v6
	v_cmp_lt_u32_e32 vcc, 15, v0
	s_and_saveexec_b64 s[0:1], vcc
	s_xor_b64 s[0:1], exec, s[0:1]
	s_cbranch_execz .LBB0_804
	v_cmp_lt_u32_e32 vcc, 18, v0
	s_nop 1
	v_cndmask_b32_e64 v1, 16, 17, vcc
	v_cmp_lt_u32_e32 vcc, 20, v0
	s_nop 1
	v_cndmask_b32_e64 v2, 0, 1, vcc
	v_cmp_lt_u32_e32 vcc, 23, v0
	s_nop 1
	v_addc_co_u32_e32 v1, vcc, v1, v2, vcc
	v_cmp_lt_u32_e32 vcc, 26, v0
	s_nop 1
	v_cndmask_b32_e64 v2, 0, 1, vcc
	v_cmp_lt_u32_e32 vcc, 30, v0
	s_nop 1
	v_addc_co_u32_e32 v1, vcc, v1, v2, vcc
	v_cmp_lt_u32_e32 vcc, 34, v0
	s_nop 1
	v_cndmask_b32_e64 v2, 0, 1, vcc
	v_cmp_lt_u32_e32 vcc, 39, v0
	s_nop 1
	v_addc_co_u32_e32 v1, vcc, v1, v2, vcc
	v_cmp_lt_u32_e32 vcc, 45, v0
	s_nop 1
	v_cndmask_b32_e64 v2, 0, 1, vcc
	v_cmp_lt_u32_e32 vcc, 51, v0
	s_nop 1
	v_addc_co_u32_e32 v1, vcc, v1, v2, vcc
	v_cmp_lt_u32_e32 vcc, 58, v0
	s_nop 1
	v_cndmask_b32_e64 v2, 0, 1, vcc
	v_cmp_lt_u32_e32 vcc, s36, v0
	s_nop 1
	v_addc_co_u32_e32 v1, vcc, v1, v2, vcc
	v_cmp_lt_u32_e32 vcc, s37, v0
	s_nop 1
	v_cndmask_b32_e64 v2, 0, 1, vcc
	v_cmp_lt_u32_e32 vcc, s39, v0
	s_nop 1
	v_addc_co_u32_e32 v1, vcc, v1, v2, vcc
	v_cmp_lt_u32_e32 vcc, s40, v0
	s_nop 1
	v_cndmask_b32_e64 v2, 0, 1, vcc
	v_cmp_lt_u32_e32 vcc, s41, v0
	s_nop 1
	v_addc_co_u32_e32 v0, vcc, v1, v2, vcc
